# rowpass: modulation gate/shift/scale vectors staged in LDS once per pass instead of 24 global loads per row
# baseline (speedup 1.0000x reference)
; DI void rowpass(const Params& p, int l, bool first, int wv, char* smem) {
;     ...
;   float* lg_post = (float*)smem;
;   float* lg_pre = (float*)smem + 2048;
;   {
;     const int t4 = (wv * 64 + lane_) * 4;
;     if (!first) *(f32x4*)(lg_post + t4) = *(const f32x4*)(p.post_g + l * DM + t4);
;     if (first || l < 3) *(f32x4*)(lg_pre + t4) = *(const f32x4*)(p.pre_g + lnext * DM + t4);
;     __syncthreads();
;   }
;     ...
;       const float* gate = p.mod + (size_t)(l * 5 + mr) * 6144 + 4096;
;       f32x4 gtv[8];
; #pragma unroll
;       for (int i = 0; i < 8; ++i) gtv[i] = *(const f32x4*)(gate + i * 256 + lane * 4);
;       f32x4 shv[8], scv[8];
;       if (l < 3) {
;         const float* shift = p.mod + (size_t)(lnext * 5 + mr) * 6144;
; #pragma unroll
;         for (int i = 0; i < 8; ++i) { shv[i] = *(const f32x4*)(shift + i * 256 + lane * 4); scv[i] = *(const f32x4*)(shift + 2048 + i * 256 + lane * 4); }
.LBB0_97:
	v_writelane_b32 v254, s24, 46
	s_add_i32 s81, s26, -3
	s_and_b32 s34, s81, 3
	s_ashr_i32 s86, s81, 2
	s_cmp_lt_i32 s86, 3
	v_writelane_b32 v254, s25, 47
	s_cselect_b64 s[82:83], -1, 0
	s_cmp_eq_u32 s86, 3
	v_writelane_b32 v254, s26, 48
	s_cselect_b64 s[76:77], -1, 0
	s_ashr_i32 s87, s86, 31
	v_writelane_b32 v254, s27, 49
	s_cmp_lt_i32 s34, 2
	s_mov_b64 s[0:1], -1
	s_cbranch_scc1 .LBB0_160
	s_cmp_gt_i32 s34, 2
	s_cbranch_scc0 .LBB0_118
	s_lshl_b32 s0, s86, 11
	s_ashr_i32 s1, s0, 31
	v_readlane_b32 s36, v253, 21
	s_lshl_b64 s[2:3], s[0:1], 2
	v_readlane_b32 s40, v253, 25
	v_mbcnt_lo_u32_b32 v0, -1, 0
	v_mbcnt_hi_u32_b32 v0, -1, v0
	v_readlane_b32 s1, v253, 37
	v_lshlrev_b32_e32 v130, 2, v0
	v_readlane_b32 s41, v253, 26
	s_add_u32 s2, s40, s2
	s_addc_u32 s3, s41, s3
	s_waitcnt vmcnt(0)
	v_lshl_add_u32 v2, s1, 8, v130
	v_ashrrev_i32_e32 v3, 31, v2
	v_lshl_add_u64 v[4:5], v[2:3], 2, s[2:3]
	global_load_dwordx4 v[4:7], v[4:5], off
	s_mul_i32 s2, s86, 0x1e000
	s_add_u32 s2, s62, s2
	s_addc_u32 s3, s63, 0
	s_add_u32 s10, s2, 0x4000
	s_addc_u32 s11, s3, 0
	v_lshl_add_u64 v[72:73], v[2:3], 2, s[10:11]
	global_load_dwordx4 v[12:15], v[72:73], off
	s_add_u32 s10, s2, 0xa000
	s_addc_u32 s11, s3, 0
	v_lshl_add_u64 v[72:73], v[2:3], 2, s[10:11]
	global_load_dwordx4 v[16:19], v[72:73], off
	s_add_u32 s10, s2, 0x10000
	s_addc_u32 s11, s3, 0
	v_lshl_add_u64 v[72:73], v[2:3], 2, s[10:11]
	global_load_dwordx4 v[20:23], v[72:73], off
	s_add_u32 s10, s2, 0x16000
	s_addc_u32 s11, s3, 0
	v_lshl_add_u64 v[72:73], v[2:3], 2, s[10:11]
	global_load_dwordx4 v[24:27], v[72:73], off
	s_add_u32 s10, s2, 0x1c000
	s_addc_u32 s11, s3, 0
	v_lshl_add_u64 v[72:73], v[2:3], 2, s[10:11]
	global_load_dwordx4 v[28:31], v[72:73], off
	v_readlane_b32 s42, v253, 27
	v_readlane_b32 s43, v253, 28
	v_readlane_b32 s44, v253, 29
	v_readlane_b32 s45, v253, 30
	v_readlane_b32 s46, v253, 31
	v_readlane_b32 s47, v253, 32
	v_readlane_b32 s48, v253, 33
	v_readlane_b32 s49, v253, 34
	v_readlane_b32 s50, v253, 35
	v_readlane_b32 s51, v253, 36
	v_readlane_b32 s40, v254, 22
	v_cndmask_b32_e64 v8, 0, 1, s[82:83]
	v_readlane_b32 s41, v254, 23
	v_readlane_b32 s42, v254, 24
	v_readlane_b32 s43, v254, 25
	v_readlane_b32 s44, v254, 26
	v_readlane_b32 s45, v254, 27
	v_readlane_b32 s46, v254, 28
	v_readlane_b32 s47, v254, 29
	v_readlane_b32 s48, v254, 30
	v_readlane_b32 s49, v254, 31
	v_readlane_b32 s50, v254, 32
	v_readlane_b32 s51, v254, 33
	v_readlane_b32 s52, v254, 34
	v_readlane_b32 s53, v254, 35
	v_readlane_b32 s54, v254, 36
	v_readlane_b32 s55, v254, 37
	v_lshlrev_b32_e32 v0, 2, v2
	v_cmp_ne_u32_e64 s[4:5], 1, v8
	s_andn2_b64 vcc, exec, s[82:83]
	v_readlane_b32 s37, v253, 22
	v_readlane_b32 s38, v253, 23
	v_readlane_b32 s39, v253, 24
	s_waitcnt vmcnt(0)
	ds_write_b128 v0, v[4:7]
	ds_write_b128 v0, v[12:15] offset:16384
	ds_write_b128 v0, v[16:19] offset:24576
	ds_write_b128 v0, v[20:23] offset:32768
	ds_write_b128 v0, v[24:27] offset:40960
	ds_write_b128 v0, v[28:31] offset:49152
	s_cbranch_vccnz .LBB0_101
	s_add_u32 s2, s2, 0x1e000
	s_addc_u32 s3, s3, 0
	s_add_u32 s10, s2, 0x0
	s_addc_u32 s11, s3, 0
	v_lshl_add_u64 v[72:73], v[2:3], 2, s[10:11]
	global_load_dwordx4 v[32:35], v[72:73], off
	s_add_u32 s10, s2, 0x2000
	s_addc_u32 s11, s3, 0
	v_lshl_add_u64 v[72:73], v[2:3], 2, s[10:11]
	global_load_dwordx4 v[36:39], v[72:73], off
	s_add_u32 s10, s2, 0x6000
	s_addc_u32 s11, s3, 0
	v_lshl_add_u64 v[72:73], v[2:3], 2, s[10:11]
	global_load_dwordx4 v[40:43], v[72:73], off
	s_add_u32 s10, s2, 0x8000
	s_addc_u32 s11, s3, 0
	v_lshl_add_u64 v[72:73], v[2:3], 2, s[10:11]
	global_load_dwordx4 v[44:47], v[72:73], off
	s_add_u32 s10, s2, 0xc000
	s_addc_u32 s11, s3, 0
	v_lshl_add_u64 v[72:73], v[2:3], 2, s[10:11]
	global_load_dwordx4 v[48:51], v[72:73], off
	s_add_u32 s10, s2, 0xe000
	s_addc_u32 s11, s3, 0
	v_lshl_add_u64 v[72:73], v[2:3], 2, s[10:11]
	global_load_dwordx4 v[52:55], v[72:73], off
	s_add_u32 s10, s2, 0x12000
	s_addc_u32 s11, s3, 0
	v_lshl_add_u64 v[72:73], v[2:3], 2, s[10:11]
	global_load_dwordx4 v[56:59], v[72:73], off
	s_add_u32 s10, s2, 0x14000
	s_addc_u32 s11, s3, 0
	v_lshl_add_u64 v[72:73], v[2:3], 2, s[10:11]
	global_load_dwordx4 v[60:63], v[72:73], off
	s_add_u32 s10, s2, 0x18000
	s_addc_u32 s11, s3, 0
	v_lshl_add_u64 v[72:73], v[2:3], 2, s[10:11]
	global_load_dwordx4 v[64:67], v[72:73], off
	s_add_u32 s10, s2, 0x1a000
	s_addc_u32 s11, s3, 0
	v_lshl_add_u64 v[72:73], v[2:3], 2, s[10:11]
	global_load_dwordx4 v[68:71], v[72:73], off
	s_add_i32 s2, s0, 0x800
	s_ashr_i32 s3, s2, 31
	s_lshl_b64 s[2:3], s[2:3], 2
	s_add_u32 s2, s52, s2
	s_addc_u32 s3, s53, s3
	v_lshl_add_u64 v[2:3], v[2:3], 2, s[2:3]
	global_load_dwordx4 v[2:5], v[2:3], off
	v_add_u32_e32 v73, 0xe000, v0
	v_add_u32_e32 v72, 0x1e000, v0
	s_waitcnt vmcnt(0)
	ds_write_b128 v0, v[2:5] offset:8192
	ds_write_b128 v73, v[32:35] offset:0
	ds_write_b128 v73, v[36:39] offset:8192
	ds_write_b128 v73, v[40:43] offset:16384
	ds_write_b128 v73, v[44:47] offset:24576
	ds_write_b128 v73, v[48:51] offset:32768
	ds_write_b128 v73, v[52:55] offset:40960
	ds_write_b128 v73, v[56:59] offset:49152
	ds_write_b128 v73, v[60:63] offset:57344
	ds_write_b128 v72, v[64:67] offset:0
	ds_write_b128 v72, v[68:71] offset:8192

; DI void rowpass(const Params& p, int l, bool first, int wv, char* smem) {
;     ...
;       const float* gate = p.mod + (size_t)(l * 5 + mr) * 6144 + 4096;
;       f32x4 gtv[8];
; #pragma unroll
;       for (int i = 0; i < 8; ++i) gtv[i] = *(const f32x4*)(gate + i * 256 + lane * 4);
;       f32x4 shv[8], scv[8];
;       if (l < 3) {
;         const float* shift = p.mod + (size_t)(lnext * 5 + mr) * 6144;
; #pragma unroll
;         for (int i = 0; i < 8; ++i) { shv[i] = *(const f32x4*)(shift + i * 256 + lane * 4); scv[i] = *(const f32x4*)(shift + 2048 + i * 256 + lane * 4); }
;       }
.LBB0_113:
	s_and_b64 s[2:3], s[2:3], exec
	s_cselect_b32 s2, 4, s24
	s_lshl_b32 s3, s2, 13
	v_add_u32_e32 v98, s3, v212
	ds_read_b128 v[122:125], v98 offset:17408
	ds_read_b128 v[118:121], v98 offset:18432
	ds_read_b128 v[126:129], v98 offset:16384
	ds_read_b128 v[114:117], v98 offset:19456
	ds_read_b128 v[110:113], v98 offset:20480
	ds_read_b128 v[106:109], v98 offset:21504
	ds_read_b128 v[102:105], v98 offset:22528
	ds_read_b128 v[98:101], v98 offset:23552
	s_and_b64 vcc, exec, s[4:5]
	s_cbranch_vccnz .LBB0_115
	s_lshl_b32 s3, s2, 14
	s_add_i32 s3, s3, 0x8000
	v_add_u32_e32 v58, s3, v212
	ds_read_b128 v[2:5], v58 offset:24576
	ds_read_b128 v[6:9], v58 offset:25600
	ds_read_b128 v[18:21], v58 offset:33792
	ds_read_b128 v[22:25], v58 offset:34816
	ds_read_b128 v[14:17], v58 offset:26624
	ds_read_b128 v[10:13], v58 offset:27648
	ds_read_b128 v[30:33], v58 offset:32768
	ds_read_b128 v[26:29], v58 offset:35840
	ds_read_b128 v[34:37], v58 offset:28672
	ds_read_b128 v[38:41], v58 offset:29696
	ds_read_b128 v[54:57], v58 offset:36864
	ds_read_b128 v[50:53], v58 offset:37888
	ds_read_b128 v[42:45], v58 offset:30720
	ds_read_b128 v[46:49], v58 offset:31744
	ds_read_b128 v[62:65], v58 offset:38912
	ds_read_b128 v[58:61], v58 offset:39936
